# P3 attention tile loop: tile j+2 LDS-DMA issue moved from the head of the tile's compute segment to mid-tile (start of the row-max/row-sum VALU stretch)
# speedup vs baseline: 1.0155x; 1.0155x over previous
; #define LAS __attribute__((address_space(3)))
; DI int crow(int r, int hi) { return (r & 3) + 8 * (r >> 2) + 4 * hi; }
; #define AT_ISSUE(slot) do { if (ABL & 8) break; _Pragma("unroll") for (int j = 0; j < NOPS; ++j) { \
;         __builtin_amdgcn_global_load_lds((const unsigned*)gp[j], (LAS unsigned*)(lds + (slot) * SLOT + loff[j]), 16, 0, 0); gp[j] += ((peflags >> j) & 1u) ? incB : incA; } } while (0)
; #define SB() __builtin_amdgcn_sched_barrier(0)
; #define LDH(dst, half, b2) do { _Pragma("unroll") for (int j = 0; j < HB; ++j) dst[j] = *(const LAS bf16x8*)(kb_ + (half) * 32 * KP + ((b2) * HB + j) * 32); } while (0)
; #define MMH(S, src, b2) do { _Pragma("unroll") for (int j = 0; j < HB; ++j) { if ((b2) == 0 && j == 0) S = MFMA32(src[0], qf[0], negm); else S = MFMA32(src[j], qf[(b2) * HB + j], S); } } while (0)
;     ...
;     for (int t = 0; t < NT; ++t) {
;         if (t + 2 < NT) AT_ISSUE(sn2);
;         const bool active = !CAUSAL || (64 * t <= qmin + 31);
;         if (active) {
;             const LAS char* kb_ = lds + sc * SLOT + r * KP + 16 * h; const LAS char* vb_ = lds + sc * SLOT + KBUF + (4 * h + q4) * VP + blk * 32 + p4 * 8;
;             f32x16 s0, s1;
;             bf16x8 fa[HB], fb[HB];
;             const unsigned va_ = (unsigned)(size_t)vb_;
;             s16x4 la[4], ha[4];
;             float m0 = 0.f, ps = 0.f; bf16x8 pf[4];
;             SB(); LDH(fa, 0, 0); SB();
; #pragma unroll
;             for (int bb = 0; bb < 2 * NBH; ++bb) {
;                 const int nb = bb + 1;
;                 if (nb < 2 * NBH) { if (nb & 1) LDH(fb, nb / NBH, nb % NBH); else LDH(fa, nb / NBH, nb % NBH); }
;                 SB();
;                 if (bb < NBH) { if (bb & 1) MMH(s0, fb, bb % NBH); else MMH(s0, fa, bb % NBH); }
;                 else          { if (bb & 1) MMH(s1, fb, bb % NBH); else MMH(s1, fa, bb % NBH); }
;                 if (bb == NBH) {
;                     if (CAUSAL && (64 * t + 31 > qmin)) {
; #pragma unroll
;                         for (int i = 0; i < 16; ++i) { const int kv = 64 * t + crow(i, h); if (kv > qpos) s0[i] = -INFINITY; } }
.LBB0_871:
	s_mov_b32 s62, s22
	s_add_i32 s22, s57, -1
	s_cmp_ge_u32 s22, s59
	s_cselect_b64 s[22:23], -1, 0
	s_mul_i32 s98, s24, 0xb400
	s_cmp_gt_i32 s58, s60
	s_cbranch_scc0 .LBB0_875
	s_and_b64 vcc, exec, s[22:23]
	s_cbranch_vccnz .LBB0_873
	s_add_i32 m0, s98, s55
	s_nop 0
	global_load_lds_dwordx4 v[192:193], off
	s_add_i32 m0, s98, s53
	v_lshl_add_u64 v[192:193], v[192:193], 0, v[176:177]
	global_load_lds_dwordx4 v[194:195], off
	s_add_i32 m0, s98, s52
	v_lshl_add_u64 v[194:195], v[194:195], 0, v[180:181]
	global_load_lds_dwordx4 v[196:197], off
	s_add_i32 m0, s98, s47
	v_lshl_add_u64 v[196:197], v[196:197], 0, v[182:183]
	global_load_lds_dwordx4 v[198:199], off
	s_add_i32 m0, s98, s46
	v_lshl_add_u64 v[198:199], v[198:199], 0, v[184:185]
	global_load_lds_dwordx4 v[200:201], off
	s_add_i32 m0, s98, s45
	v_lshl_add_u64 v[200:201], v[200:201], 0, v[186:187]
	global_load_lds_dwordx4 v[202:203], off
	v_lshl_add_u64 v[202:203], v[202:203], 0, v[188:189]
.LBB0_873:
	s_cmp_ge_u32 s57, s56
	s_cbranch_scc0 .LBB0_887
	s_branch .LBB0_891
.LBB0_875:
	s_mul_i32 s24, s62, 0xb400
	s_add_i32 s24, s24, 0
	v_add_u32_e32 v80, s24, v191
	v_add_u32_e32 v168, v80, v190
	ds_read_b128 v[80:83], v168
	ds_read_b128 v[84:87], v168 offset:32
	ds_read_b128 v[88:91], v168 offset:64
	ds_read_b128 v[92:95], v168 offset:96
	s_add_i32 s25, s58, 31
	s_cmp_le_i32 s25, s54
	s_waitcnt lgkmcnt(0)
	v_mfma_f32_32x32x16_bf16 v[96:111], v[80:83], v[112:115], v[64:79]
	v_mfma_f32_32x32x16_bf16 v[96:111], v[84:87], v[116:119], v[96:111]
	ds_read_b128 v[80:83], v168 offset:128
	ds_read_b128 v[84:87], v168 offset:160
	v_mfma_f32_32x32x16_bf16 v[96:111], v[88:91], v[120:123], v[96:111]
	v_mfma_f32_32x32x16_bf16 v[96:111], v[92:95], v[124:127], v[96:111]
	ds_read_b128 v[88:91], v168 offset:192
	ds_read_b128 v[92:95], v168 offset:224
	s_waitcnt lgkmcnt(0)
	v_mfma_f32_32x32x16_bf16 v[96:111], v[80:83], v[128:131], v[96:111]
	v_mfma_f32_32x32x16_bf16 v[96:111], v[84:87], v[132:135], v[96:111]
	ds_read_b128 v[80:83], v168 offset:256
	ds_read_b128 v[84:87], v168 offset:288
	v_mfma_f32_32x32x16_bf16 v[96:111], v[88:91], v[136:139], v[96:111]
	v_mfma_f32_32x32x16_bf16 v[96:111], v[92:95], v[140:143], v[96:111]
	ds_read_b128 v[88:91], v168 offset:320
	ds_read_b128 v[92:95], v168 offset:352
	s_waitcnt lgkmcnt(0)
	v_mfma_f32_32x32x16_bf16 v[96:111], v[80:83], v[144:147], v[96:111]
	v_mfma_f32_32x32x16_bf16 v[96:111], v[84:87], v[148:151], v[96:111]
	ds_read_b128 v[170:173], v168 offset:12800
	ds_read_b128 v[216:219], v168 offset:12832
	v_mfma_f32_32x32x16_bf16 v[96:111], v[88:91], v[152:155], v[96:111]
	v_mfma_f32_32x32x16_bf16 v[96:111], v[92:95], v[156:159], v[96:111]
	ds_read_b128 v[164:167], v168 offset:12864
	ds_read_b128 v[160:163], v168 offset:12896
	s_nop 7
	v_add_u32_e32 v204, s58, v210
	s_waitcnt lgkmcnt(0)
	v_mfma_f32_32x32x16_bf16 v[80:95], v[170:173], v[112:115], v[64:79]
	v_mfma_f32_32x32x16_bf16 v[80:95], v[216:219], v[116:119], v[80:95]
	s_cbranch_scc1 .LBB0_877
	v_cmp_lt_i32_e32 vcc, v204, v209
	v_add_u32_e32 v169, 2, v204
	s_nop 0
	v_cndmask_b32_e32 v97, v208, v97, vcc
	v_cmp_le_i32_e32 vcc, v204, v209
	s_nop 1
	v_cndmask_b32_e32 v96, v208, v96, vcc
	v_cmp_le_i32_e32 vcc, v169, v209
	v_add_u32_e32 v169, 3, v204
	s_nop 0
	v_cndmask_b32_e32 v98, v208, v98, vcc
	v_cmp_le_i32_e32 vcc, v169, v209
	v_add_u32_e32 v169, 8, v204
	s_nop 0
	v_cndmask_b32_e32 v99, v208, v99, vcc
	v_cmp_le_i32_e32 vcc, v169, v209
	v_add_u32_e32 v169, 9, v204
	s_nop 0
	v_cndmask_b32_e32 v100, v208, v100, vcc
	v_cmp_le_i32_e32 vcc, v169, v209
	v_add_u32_e32 v169, 10, v204
	s_nop 0
	v_cndmask_b32_e32 v101, v208, v101, vcc
	v_cmp_le_i32_e32 vcc, v169, v209
	v_add_u32_e32 v169, 11, v204
	s_nop 0
	v_cndmask_b32_e32 v102, v208, v102, vcc
	v_cmp_le_i32_e32 vcc, v169, v209
	v_add_u32_e32 v169, 16, v204
	s_nop 0
	v_cndmask_b32_e32 v103, v208, v103, vcc
	v_cmp_le_i32_e32 vcc, v169, v209
	v_add_u32_e32 v169, 17, v204
	s_nop 0
	v_cndmask_b32_e32 v104, v208, v104, vcc
	v_cmp_le_i32_e32 vcc, v169, v209
	v_add_u32_e32 v169, 18, v204
	s_nop 0
	v_cndmask_b32_e32 v105, v208, v105, vcc
	v_cmp_le_i32_e32 vcc, v169, v209
	v_add_u32_e32 v169, 19, v204
	s_nop 0
	v_cndmask_b32_e32 v106, v208, v106, vcc
	v_cmp_le_i32_e32 vcc, v169, v209
	v_add_u32_e32 v169, 24, v204
	s_nop 0
	v_cndmask_b32_e32 v107, v208, v107, vcc
	v_cmp_le_i32_e32 vcc, v169, v209
	v_add_u32_e32 v169, 25, v204
	s_nop 0
	v_cndmask_b32_e32 v108, v208, v108, vcc
	v_cmp_le_i32_e32 vcc, v169, v209
	v_add_u32_e32 v169, 26, v204
	s_nop 0
	v_cndmask_b32_e32 v109, v208, v109, vcc
	v_cmp_le_i32_e32 vcc, v169, v209
	v_add_u32_e32 v169, 27, v204
	s_nop 0
	v_cndmask_b32_e32 v110, v208, v110, vcc
	v_cmp_le_i32_e32 vcc, v169, v209
	s_nop 1
	v_cndmask_b32_e32 v111, v208, v111, vcc

; #define AT_ISSUE(slot) do { if (ABL & 8) break; _Pragma("unroll") for (int j = 0; j < NOPS; ++j) { \
;         __builtin_amdgcn_global_load_lds((const unsigned*)gp[j], (LAS unsigned*)(lds + (slot) * SLOT + loff[j]), 16, 0, 0); gp[j] += ((peflags >> j) & 1u) ? incB : incA; } } while (0)
;     ...
;         if (t + 2 < NT) AT_ISSUE(sn2);
.LBB0_879:
	s_and_b64 vcc, exec, s[22:23]
	s_cbranch_vccnz .Lat_dma_done
	s_add_i32 m0, s98, s55
	s_nop 0
	global_load_lds_dwordx4 v[192:193], off
	s_add_i32 m0, s98, s53
	v_lshl_add_u64 v[192:193], v[192:193], 0, v[176:177]
	global_load_lds_dwordx4 v[194:195], off
	s_add_i32 m0, s98, s52
	v_lshl_add_u64 v[194:195], v[194:195], 0, v[180:181]
	global_load_lds_dwordx4 v[196:197], off
	s_add_i32 m0, s98, s47
	v_lshl_add_u64 v[196:197], v[196:197], 0, v[182:183]
	global_load_lds_dwordx4 v[198:199], off
	s_add_i32 m0, s98, s46
	v_lshl_add_u64 v[198:199], v[198:199], 0, v[184:185]
	global_load_lds_dwordx4 v[200:201], off
	s_add_i32 m0, s98, s45
	v_lshl_add_u64 v[200:201], v[200:201], 0, v[186:187]
	global_load_lds_dwordx4 v[202:203], off
	v_lshl_add_u64 v[202:203], v[202:203], 0, v[188:189]
